# in-proj slack workgroups start only ~3 us late (instead of 8-16 us): tests whether the gain comes from a cold-start effect
# speedup vs baseline: 1.0051x; 1.0051x over previous
; __device__ __forceinline__ int opaque_tid() { int t = threadIdx.x; asm volatile("" : "+v"(t)); return t; }
; template <class Epi, class Sched>
; __device__ __forceinline__ void gemm_phase(LAS unsigned char* lds, const Gemm g, const Sched& S, const Epi& E) {
;     const int tid = opaque_tid(), wid = __builtin_amdgcn_readfirstlane(tid >> 6), lane = tid & 63, wr = wid >> 2, wc = wid & 3, fr = lane & 15, fq = lane >> 4;
;     const int K = g.K, nt = K / BK;
;     unsigned voffA[2], voffB[2];
; #pragma unroll
;     for (int i = 0; i < 2; ++i) { int R, C; stage_rc(tid * 16 + i * 8192, R, C); const int Rb = Epi::PERM ? ((R & ~31) + perm32(R & 31)) : R;
;         voffA[i] = (unsigned)(R * K + C) * 2u; voffB[i] = (unsigned)(Rb * K + C) * 2u; }
;     ...
;     if (!S.next(0, cur)) return;
.LBB0_180:
	s_or_b64 exec, exec, s[0:1]
	v_readlane_b32 s0, v240, 24
	v_readlane_b32 s1, v240, 25
	s_mov_b32 s1, s3
	v_writelane_b32 v240, s0, 24
	s_waitcnt lgkmcnt(0)
	v_mov_b32_e32 v0, v135
	v_writelane_b32 v240, s1, 25
	v_readlane_b32 s0, v243, 39
	v_readlane_b32 s1, v243, 40
	s_barrier
	s_andn2_b64 vcc, exec, s[0:1]
	v_readfirstlane_b32 s5, v0
	s_cbranch_vccnz .LBB0_192
	v_lshlrev_b32_e32 v4, 4, v0
	v_add_u32_e32 v2, 0x2000, v4
	v_ashrrev_i32_e32 v1, 31, v2
	v_lshrrev_b32_e32 v1, 22, v1
	v_add_u32_e32 v1, v2, v1
	v_ashrrev_i32_e32 v1, 10, v1
	v_mul_i32_i24_e32 v3, 0x400, v1
	v_sub_u32_e32 v2, v2, v3
	v_lshrrev_b32_e32 v3, 4, v2
	v_bitop3_b32 v3, v3, v2, 32 bitop3:0x6c
	v_ashrrev_i32_e32 v2, 31, v3
	v_lshrrev_b32_e32 v2, 26, v2
	v_add_u32_e32 v5, v3, v2
	v_lshlrev_b32_e32 v6, 3, v1
	v_ashrrev_i32_e32 v2, 6, v5
	v_and_b32_e32 v6, -16, v6
	v_add_u32_e32 v6, v2, v6
	v_and_b32_e32 v7, 3, v2
	s_mov_b32 s2, 0x1fffe0
	v_lshrrev_b32_e32 v9, 2, v6
	v_lshlrev_b32_e32 v10, 1, v6
	v_and_b32_e32 v5, 0xc0, v5
	v_and_or_b32 v7, v6, s2, v7
	v_and_b32_e32 v9, 4, v9
	v_and_b32_e32 v10, 24, v10
	v_sub_u32_e32 v3, v3, v5
	v_or3_b32 v7, v7, v9, v10
	v_lshlrev_b32_e32 v9, 5, v1
	v_ashrrev_i16_sdwa v3, v176, sext(v3) dst_sel:DWORD dst_unused:UNUSED_PAD src0_sel:DWORD src1_sel:BYTE_0
	v_and_b32_e32 v9, 32, v9
	v_bfe_i32 v3, v3, 0, 16
	v_add_lshl_u32 v5, v9, v3, 1
	v_lshl_add_u32 v140, v7, 11, v5
	v_lshl_add_u32 v142, v6, 11, v5
	v_bfe_i32 v5, v0, 27, 1
	v_lshrrev_b32_e32 v5, 22, v5
	v_add_u32_e32 v5, v4, v5
	v_and_b32_e32 v5, 0xfffffc00, v5
	v_sub_u32_e32 v4, v4, v5
	v_lshrrev_b32_e32 v5, 4, v4
	v_bitop3_b32 v6, v5, v4, 32 bitop3:0x6c
	v_ashrrev_i32_e32 v5, 31, v0
	v_lshrrev_b32_e32 v5, 26, v5
	v_ashrrev_i32_e32 v4, 31, v4
	v_add_u32_e32 v5, v0, v5
	v_lshrrev_b32_e32 v4, 26, v4
	v_ashrrev_i32_e32 v5, 6, v5
	v_add_u32_e32 v4, v6, v4
	v_lshlrev_b32_e32 v7, 3, v5
	v_ashrrev_i32_e32 v4, 6, v4
	v_and_b32_e32 v7, -16, v7
	v_add_u32_e32 v7, v4, v7
	v_readlane_b32 s0, v240, 24
	v_and_b32_e32 v9, 3, v4
	v_lshrrev_b32_e32 v10, 2, v7
	v_lshlrev_b32_e32 v11, 1, v7
	s_mul_i32 s0, s0, 0x700000
	v_and_or_b32 v9, v7, s2, v9
	v_and_b32_e32 v10, 4, v10
	v_and_b32_e32 v11, 24, v11
	v_readlane_b32 s1, v240, 25
	s_add_u32 s6, s62, s0
	v_or3_b32 v9, v9, v10, v11
	v_mul_i32_i24_e32 v11, 64, v4
	s_addc_u32 s7, s63, 0
	s_ashr_i32 s1, s5, 6
	v_sub_u32_e32 v6, v6, v11
	s_ashr_i32 s0, s5, 8
	s_lshl_b32 s8, s1, 10
	v_lshlrev_b32_e32 v10, 5, v5
	v_ashrrev_i16_sdwa v6, v176, sext(v6) dst_sel:DWORD dst_unused:UNUSED_PAD src0_sel:DWORD src1_sel:BYTE_0
	v_readlane_b32 s10, v241, 18
	v_and_b32_e32 v10, 32, v10
	v_bfe_i32 v6, v6, 0, 16
	v_readlane_b32 s11, v241, 19
	s_add_u32 s66, s6, s10
	v_add_lshl_u32 v10, v10, v6, 1
	s_addc_u32 s67, s7, s11
	s_add_i32 s9, s8, 16
	v_lshl_add_u32 v144, v9, 11, v10
	s_cmp_lt_u32 s92, 0x70
	s_cbranch_scc1 .Lds184_x
	s_cmp_lg_u32 s46, 0x100
	s_cbranch_scc1 .Lds184_x
	s_sub_u32 s98, s92, 0x70
	s_mov_b32 s98, 0
	s_add_u32 s98, s98, 3
	s_min_u32 s98, s98, 20
